# conv2d item loop: first six halo loads issued together into fresh VGPRs with counted waits instead of three serialized vmcnt(0) round trips
# speedup vs baseline: 1.0180x; 1.0180x over previous
; __device__ __forceinline__ void conv2d_phase(const Frame& F, int l, bool with_ctx, bool dry) {
;     ...
;     for (int it = gw; it < total; it += NGW) {
;         const bool isctx = it >= NLAT;
;         const int q = isctx ? it - NLAT : it, cc = q % 11, seg = q / 11;
;         int tok0, c0, wlim; bool up_ok, dn_ok;
;         if (!isctx) { const int b = seg >> 10, r = (seg >> 3) & 127; c0 = (seg & 7) * 8; tok0 = b * SEQ + r * GRIDW + c0; wlim = GRIDW; up_ok = r > 0; dn_ok = r < SEQ / GRIDW - 1; }
;         else { const int b = seg >> 5; c0 = (seg & 31) * 8; tok0 = ML + b * CTXL + c0; wlim = CTXL; up_ok = false; dn_ok = false; }
;         const int ch = cc * 256 + lane * 4;
;         const float* wq = W9 + ch;
;         f32x4 w[9];
; #pragma unroll
;         for (int k = 0; k < 9; ++k) w[k] = *(const f32x4*)(wq + (size_t)k * FFN);
;         const f32x4 bias4 = *(const f32x4*)(Bc + ch);
;         const bf16_t* ubase = UV + (size_t)tok0 * NUP + ch;
;         u32x2 u[3][10];
; #pragma unroll
;         for (int dy = 0; dy < 3; ++dy) {
;             const bool rok = dy == 1 ? true : (dy == 0 ? up_ok : dn_ok);
; #pragma unroll
;             for (int j = 0; j < 10; ++j) {
;                 const int col = c0 - 1 + j; const bool ok = rok && col >= 0 && col < wlim;
;                 const unsigned msk = (unsigned)-(int)ok;
;                 const long off = (long)(((dy - 1) * GRIDW + (j - 1)) & (int)msk) * NUP;
;                 const u32x2 t = *(const u32x2*)(ubase + off);
;                 u[dy][j] = (u32x2){t.x & msk, t.y & msk};
;             }
;         }
.LBB0_2037:
	s_add_i32 s4, s6, -1
	s_or_b32 s5, s6, 1
	s_or_b32 s8, s6, 2
	s_or_b32 s9, s6, 3
	s_or_b32 s10, s6, 4
	s_or_b32 s11, s6, 5
	s_or_b32 s17, s6, 6
	s_or_b32 s28, s6, 7
	s_add_i32 s16, s6, 8
	s_cmp_lt_u32 s4, s7
	s_cselect_b64 s[0:1], -1, 0
	s_and_b64 s[0:1], s[0:1], exec
	s_cselect_b32 s75, -1, 0
	s_cmp_lt_u32 s16, s7
	s_cselect_b64 s[38:39], -1, 0
	s_and_b64 s[0:1], s[38:39], exec
	s_cselect_b32 s16, 0x16000, 0
	s_cmp_lt_u32 s28, s7
	s_cselect_b64 s[40:41], -1, 0
	s_and_b64 s[0:1], s[40:41], exec
	s_cselect_b32 s92, 0x13400, 0
	s_cmp_lt_u32 s17, s7
	s_cselect_b64 s[42:43], -1, 0
	s_and_b64 s[0:1], s[42:43], exec
	s_cselect_b32 s68, 0x10800, 0
	s_cmp_lt_u32 s11, s7
	s_cselect_b64 s[44:45], -1, 0
	s_and_b64 s[0:1], s[44:45], exec
	s_cselect_b32 s66, 0xdc00, 0
	s_cmp_lt_u32 s10, s7
	s_cselect_b64 s[76:77], -1, 0
	s_and_b64 s[0:1], s[76:77], exec
	s_cselect_b32 s10, 0xb000, 0
	s_cmp_lt_u32 s9, s7
	s_cselect_b64 s[82:83], -1, 0
	s_and_b64 s[0:1], s[82:83], exec
	s_cselect_b32 s62, 0x8400, 0
	s_cmp_lt_u32 s8, s7
	s_cselect_b64 s[64:65], -1, 0
	s_and_b64 s[0:1], s[64:65], exec
	s_cselect_b32 s88, 0x5800, 0
	s_cmp_lt_u32 s5, s7
	s_cselect_b64 vcc, -1, 0
	s_and_b64 s[0:1], vcc, exec
	s_cselect_b32 s28, 0x2c00, 0
	s_cmp_lt_u32 s4, s7
	s_cselect_b64 s[0:1], -1, 0
	s_mul_i32 s3, s3, 11
	s_and_b64 s[4:5], s[0:1], exec
	s_cselect_b32 s74, 0xffffd400, 0
	s_sub_i32 s2, s2, s3
	v_lshl_add_u32 v42, s2, 8, v0
	v_ashrrev_i32_e32 v43, 31, v42
	v_readlane_b32 s2, v255, 21
	v_lshlrev_b64 v[38:39], 2, v[42:43]
	v_readlane_b32 s3, v255, 22
	v_readlane_b32 s4, v254, 19
	v_readlane_b32 s5, v254, 20
	s_waitcnt lgkmcnt(0)
	v_lshl_add_u64 v[2:3], s[2:3], 0, v[38:39]
	s_movk_i32 s2, 0x2000
	v_add_co_u32_e64 v4, s[2:3], s2, v2
	s_mov_b32 s11, s29
	s_nop 0
	v_addc_co_u32_e64 v5, s[2:3], 0, v3, s[2:3]
	s_movk_i32 s2, 0x5000
	s_nop 0
	v_add_co_u32_e64 v6, s[2:3], s2, v2
	s_mov_b32 s89, s29
	s_nop 0
	v_addc_co_u32_e64 v7, s[2:3], 0, v3, s[2:3]
	s_mov_b32 s2, 0x8000
	s_nop 0
	v_add_co_u32_e64 v8, s[2:3], s2, v2
	s_mov_b32 s63, s29
	s_nop 0
	v_addc_co_u32_e64 v9, s[2:3], 0, v3, s[2:3]
	s_mov_b32 s2, 0xb000
	s_nop 0
	v_add_co_u32_e64 v10, s[2:3], s2, v2
	s_mov_b32 s67, s29
	s_nop 0
	v_addc_co_u32_e64 v11, s[2:3], 0, v3, s[2:3]
	s_mov_b32 s2, 0xd000
	s_nop 0
	v_add_co_u32_e64 v12, s[2:3], s2, v2
	s_mov_b32 s69, s29
	s_nop 0
	v_addc_co_u32_e64 v13, s[2:3], 0, v3, s[2:3]
	s_mov_b32 s2, 0x10000
	s_nop 0
	v_add_co_u32_e64 v14, s[2:3], s2, v2
	s_mov_b32 s93, s29
	s_nop 0
	v_addc_co_u32_e64 v15, s[2:3], 0, v3, s[2:3]
	s_mov_b32 s2, 0x13000
	s_nop 0
	v_add_co_u32_e64 v40, s[2:3], s2, v2
	s_mov_b32 s17, s29
	s_nop 0
	v_addc_co_u32_e64 v41, s[2:3], 0, v3, s[2:3]
	s_mov_b32 s2, 0x16000
	s_nop 0
	v_add_co_u32_e64 v44, s[2:3], s2, v2
	s_mov_b32 s36, 0x3f07dc22
	s_nop 0
	v_addc_co_u32_e64 v45, s[2:3], 0, v3, s[2:3]
	s_mul_i32 s2, s27, 0x2c00
	s_mul_hi_i32 s3, s27, 0x2c00
	s_add_u32 s2, s4, s2
	s_addc_u32 s3, s5, s3
	s_and_b64 s[4:5], s[70:71], s[0:1]
	v_lshl_add_u64 v[68:69], v[42:43], 1, s[2:3]
	s_and_b64 s[2:3], s[4:5], exec
	s_cselect_b32 s3, -1, 0
	s_cselect_b32 s2, 0xfff4d400, 0
	v_lshl_add_u64 v[16:17], v[68:69], 0, s[2:3]
	global_load_dwordx2 v[16:17], v[16:17], off
	s_cmp_lt_u32 s6, s7
	s_cselect_b64 s[2:3], -1, 0
	s_and_b64 s[6:7], s[70:71], s[2:3]
	s_and_b64 s[8:9], s[6:7], exec
	s_cselect_b32 s9, -1, 0
	s_cselect_b32 s8, 0xfff50000, 0
	v_lshl_add_u64 v[18:19], v[68:69], 0, s[8:9]
	s_and_b64 s[8:9], s[70:71], vcc
	s_and_b64 s[72:73], s[8:9], exec
	s_cselect_b32 s73, -1, 0
	s_cselect_b32 s72, 0xfff52c00, 0
	v_lshl_add_u64 v[20:21], v[68:69], 0, s[72:73]
	s_and_b64 s[46:47], s[70:71], s[64:65]
	s_and_b64 s[72:73], s[46:47], exec
	s_cselect_b32 s73, -1, 0
	s_cselect_b32 s72, 0xfff55800, 0
	v_lshl_add_u64 v[46:47], v[68:69], 0, s[72:73]
	v_lshl_add_u64 v[70:71], v[68:69], 0, s[10:11]
	v_lshl_add_u64 v[62:63], v[68:69], 0, s[88:89]
	v_lshl_add_u64 v[64:65], v[68:69], 0, s[62:63]
	s_mov_b64 s[50:51], s[46:47]
	s_mov_b32 s46, 0xbf38aa3b
	s_mov_b64 s[88:89], s[44:45]
	global_load_dwordx2 v[150:151], v[18:19], off
	global_load_dwordx2 v[152:153], v[20:21], off
	v_lshl_add_u64 v[154:155], v[68:69], 0, s[74:75]
	v_lshl_add_u64 v[162:163], v[68:69], 0, s[28:29]
	global_load_dwordx2 v[156:157], v[154:155], off
	global_load_dwordx2 v[158:159], v[68:69], off
	global_load_dwordx2 v[160:161], v[162:163], off
	s_waitcnt vmcnt(5)
	v_cndmask_b32_e64 v109, 0, v16, s[4:5]
	v_cndmask_b32_e64 v108, 0, v17, s[4:5]
	v_lshlrev_b32_e32 v110, 16, v109
	v_and_b32_e32 v111, 0xffff0000, v109
	s_waitcnt vmcnt(4)
	v_cndmask_b32_e64 v107, 0, v150, s[6:7]
	v_cndmask_b32_e64 v106, 0, v151, s[6:7]
	v_lshlrev_b32_e32 v116, 16, v107
	v_and_b32_e32 v117, 0xffff0000, v107
	v_lshlrev_b32_e32 v118, 16, v106
	v_and_b32_e32 v119, 0xffff0000, v106
	s_waitcnt vmcnt(3)
	v_cndmask_b32_e64 v105, 0, v152, s[8:9]
	v_cndmask_b32_e64 v104, 0, v153, s[8:9]
	s_and_b64 s[8:9], s[70:71], s[82:83]
	s_and_b64 s[4:5], s[8:9], exec
	s_cselect_b32 s5, -1, 0
	s_cselect_b32 s4, 0xfff58400, 0
	s_and_b64 s[6:7], s[70:71], s[76:77]
	v_lshl_add_u64 v[48:49], v[68:69], 0, s[4:5]
	s_and_b64 s[4:5], s[6:7], exec
	s_cselect_b32 s5, -1, 0
	s_cselect_b32 s4, 0xfff5b000, 0
	v_lshl_add_u64 v[50:51], v[68:69], 0, s[4:5]
	s_and_b64 s[4:5], s[70:71], s[44:45]
	v_writelane_b32 v255, s4, 27
	v_lshlrev_b32_e32 v112, 16, v104
	v_and_b32_e32 v113, 0xffff0000, v104
	v_writelane_b32 v255, s5, 28
	s_and_b64 s[4:5], s[4:5], exec
	s_cselect_b32 s5, -1, 0
	s_cselect_b32 s4, 0xfff5dc00, 0
	v_lshl_add_u64 v[52:53], v[68:69], 0, s[4:5]
	s_and_b64 s[4:5], s[70:71], s[42:43]
	v_writelane_b32 v255, s4, 25
	s_mov_b64 s[74:75], s[42:43]
	s_waitcnt vmcnt(2)
; __device__ __forceinline__ void conv2d_phase(const Frame& F, int l, bool with_ctx, bool dry) {
;     ...
;         const float* wq = W9 + ch;
;         f32x4 w[9];
; #pragma unroll
;         for (int k = 0; k < 9; ++k) w[k] = *(const f32x4*)(wq + (size_t)k * FFN);
;         const f32x4 bias4 = *(const f32x4*)(Bc + ch);
;         const bf16_t* ubase = UV + (size_t)tok0 * NUP + ch;
;         u32x2 u[3][10];
; #pragma unroll
;         for (int dy = 0; dy < 3; ++dy) {
;             const bool rok = dy == 1 ? true : (dy == 0 ? up_ok : dn_ok);
; #pragma unroll
;             for (int j = 0; j < 10; ++j) {
;                 const int col = c0 - 1 + j; const bool ok = rok && col >= 0 && col < wlim;
;                 const unsigned msk = (unsigned)-(int)ok;
;                 const long off = (long)(((dy - 1) * GRIDW + (j - 1)) & (int)msk) * NUP;
;                 const u32x2 t = *(const u32x2*)(ubase + off);
;                 u[dy][j] = (u32x2){t.x & msk, t.y & msk};
;             }
;         }
;         u32x2 vv[8];
; #pragma unroll
;         for (int t = 0; t < 8; ++t) vv[t] = *(const u32x2*)(ubase + (size_t)t * NUP + FFN);
	v_cndmask_b32_e64 v123, 0, v156, s[0:1]
	v_writelane_b32 v255, s5, 26
	s_and_b64 s[4:5], s[4:5], exec
	s_cselect_b32 s5, -1, 0
	s_cselect_b32 s4, 0xfff60800, 0
	v_lshl_add_u64 v[54:55], v[68:69], 0, s[4:5]
	s_and_b64 s[4:5], s[70:71], s[40:41]
	v_writelane_b32 v255, s4, 23
	v_cndmask_b32_e64 v120, 0, v157, s[0:1]
	s_waitcnt vmcnt(1)
	v_cndmask_b32_e64 v121, 0, v158, s[2:3]
	v_writelane_b32 v255, s5, 24
	s_and_b64 s[4:5], s[4:5], exec
	s_cselect_b32 s5, -1, 0
	s_cselect_b32 s4, 0xfff63400, 0
	s_and_b64 s[72:73], s[70:71], s[38:39]
	v_lshl_add_u64 v[56:57], v[68:69], 0, s[4:5]
	s_and_b64 s[4:5], s[72:73], exec
	s_cselect_b32 s5, -1, 0
	s_cselect_b32 s4, 0xfff66000, 0
	s_and_b64 s[0:1], s[30:31], s[0:1]
	v_lshl_add_u64 v[58:59], v[68:69], 0, s[4:5]
	s_and_b64 s[4:5], s[0:1], exec
	v_cndmask_b32_e64 v122, 0, v159, s[2:3]
	s_cselect_b32 s28, 0xad400, 0
	s_and_b64 s[2:3], s[30:31], s[2:3]
	s_and_b64 s[4:5], s[2:3], exec
	v_lshl_add_u64 v[16:17], v[68:69], 0, s[28:29]
	s_cselect_b32 s28, 0xb0000, 0
	global_load_dwordx2 v[72:73], v[16:17], off
	v_lshl_add_u64 v[16:17], v[68:69], 0, s[28:29]
	global_load_dwordx2 v[74:75], v[16:17], off
	s_waitcnt vmcnt(2)
	v_cndmask_b32_e32 v115, 0, v160, vcc
	v_cndmask_b32_e32 v114, 0, v161, vcc
	s_and_b64 vcc, s[30:31], vcc
	s_and_b64 s[4:5], vcc, exec
	s_cselect_b32 s28, 0xb2c00, 0
	v_lshl_add_u64 v[16:17], v[68:69], 0, s[28:29]
	global_load_dwordx2 v[76:77], v[16:17], off
	global_load_dwordx4 v[34:37], v[2:3], off
	global_load_dwordx4 v[18:21], v[4:5], off offset:3072
	global_load_dwordx4 v[22:25], v[6:7], off offset:2048
	global_load_dwordx4 v[26:29], v[8:9], off offset:1024
	global_load_dwordx4 v[30:33], v[10:11], off
	s_nop 0
	global_load_dwordx4 v[10:13], v[12:13], off offset:3072
	s_nop 0
	global_load_dwordx4 v[14:17], v[14:15], off offset:2048
	s_nop 0
	global_load_dwordx4 v[2:5], v[40:41], off offset:1024
	global_load_dwordx4 v[6:9], v[44:45], off
	v_readlane_b32 s4, v255, 55
	v_readlane_b32 s5, v255, 56
	v_lshlrev_b32_e32 v138, 16, v123
	v_and_b32_e32 v139, 0xffff0000, v123
	v_lshl_add_u64 v[38:39], s[4:5], 0, v[38:39]
	s_and_b64 s[4:5], s[30:31], s[64:65]
	global_load_dwordx4 v[38:41], v[38:39], off
	s_nop 0
	global_load_dwordx2 v[92:93], v[46:47], off
	global_load_dwordx2 v[80:81], v[48:49], off
	global_load_dwordx2 v[66:67], v[50:51], off
	global_load_dwordx2 v[60:61], v[52:53], off
	s_nop 0
	global_load_dwordx2 v[54:55], v[54:55], off
	s_nop 0
	global_load_dwordx2 v[48:49], v[56:57], off
	global_load_dwordx2 v[44:45], v[58:59], off
	global_load_dwordx2 v[94:95], v[62:63], off
	global_load_dwordx2 v[82:83], v[64:65], off
	s_nop 0
	global_load_dwordx2 v[70:71], v[70:71], off
	v_lshl_add_u64 v[46:47], v[68:69], 0, s[66:67]
	global_load_dwordx2 v[64:65], v[46:47], off
	v_lshlrev_b32_e32 v140, 16, v120
	v_and_b32_e32 v141, 0xffff0000, v120
	v_lshlrev_b32_e32 v120, 16, v121
	v_and_b32_e32 v121, 0xffff0000, v121
	v_lshlrev_b32_e32 v104, 16, v115
	v_lshlrev_b32_e32 v124, 16, v122
	v_and_b32_e32 v125, 0xffff0000, v122
	v_lshlrev_b32_e32 v106, 16, v114
	v_and_b32_e32 v107, 0xffff0000, v114
	s_mov_b64 s[66:67], s[38:39]
	s_mov_b64 s[70:71], s[40:41]
	s_waitcnt vmcnt(23)
	v_cndmask_b32_e64 v133, 0, v72, s[0:1]
	v_cndmask_b32_e64 v132, 0, v73, s[0:1]
	s_and_b64 s[0:1], s[4:5], exec
	s_waitcnt vmcnt(22)
	v_cndmask_b32_e64 v126, 0, v74, s[2:3]
	v_cndmask_b32_e64 v127, 0, v75, s[2:3]
	s_cselect_b32 s28, 0xb5800, 0
	s_and_b64 s[2:3], s[30:31], s[82:83]
	s_and_b64 s[0:1], s[2:3], exec
	v_lshl_add_u64 v[50:51], v[68:69], 0, s[28:29]
	s_cselect_b32 s28, 0xb8400, 0
	s_and_b64 s[0:1], s[30:31], s[76:77]
	s_and_b64 s[10:11], s[0:1], exec
	global_load_dwordx2 v[100:101], v[50:51], off
	v_lshl_add_u64 v[50:51], v[68:69], 0, s[28:29]
	s_cselect_b32 s28, 0xbb000, 0
	s_and_b64 s[62:63], s[30:31], s[44:45]
	v_lshl_add_u64 v[46:47], v[68:69], 0, s[68:69]
	s_and_b64 s[10:11], s[62:63], exec
	global_load_dwordx2 v[58:59], v[46:47], off
	global_load_dwordx2 v[90:91], v[50:51], off
	v_lshl_add_u64 v[50:51], v[68:69], 0, s[28:29]
	s_cselect_b32 s28, 0xbdc00, 0
	s_and_b64 s[68:69], s[30:31], s[42:43]
	v_lshl_add_u64 v[46:47], v[68:69], 0, s[92:93]
	s_and_b64 s[10:11], s[68:69], exec
	global_load_dwordx2 v[52:53], v[46:47], off
	global_load_dwordx2 v[84:85], v[50:51], off
	v_lshl_add_u64 v[46:47], v[68:69], 0, s[16:17]
	v_lshl_add_u64 v[50:51], v[68:69], 0, s[28:29]
	s_cselect_b32 s28, 0xc0800, 0
	s_and_b64 s[16:17], s[30:31], s[40:41]
	s_and_b64 s[10:11], s[16:17], exec
	global_load_dwordx2 v[46:47], v[46:47], off
	s_waitcnt vmcnt(27)
	v_cndmask_b32_e32 v131, 0, v76, vcc
	global_load_dwordx2 v[72:73], v[50:51], off
	v_lshl_add_u64 v[50:51], v[68:69], 0, s[28:29]
	s_cselect_b32 s28, 0xc3400, 0
	s_and_b64 s[10:11], s[30:31], s[38:39]
	s_and_b64 s[30:31], s[10:11], exec
	global_load_dwordx2 v[62:63], v[50:51], off
	v_lshl_add_u64 v[50:51], v[68:69], 0, s[28:29]
	s_cselect_b32 s28, 0xc6000, 0
	global_load_dwordx2 v[56:57], v[50:51], off
	v_lshl_add_u64 v[50:51], v[68:69], 0, s[28:29]
	s_movk_i32 s28, 0x1000
	v_cndmask_b32_e32 v130, 0, v77, vcc
	v_add_co_u32_e32 v74, vcc, s28, v68
	s_movk_i32 s28, 0x4000
	s_nop 0
	v_addc_co_u32_e32 v75, vcc, 0, v69, vcc
	global_load_dwordx2 v[102:103], v[74:75], off offset:1536
	v_add_co_u32_e32 v74, vcc, s28, v68
	s_movk_i32 s28, 0x6000
	s_nop 0
	v_addc_co_u32_e32 v75, vcc, 0, v69, vcc
	global_load_dwordx2 v[50:51], v[50:51], off
	s_waitcnt vmcnt(22)
; __device__ __forceinline__ unsigned pk2(float lo, float hi) { const f32x2 v = {lo, hi}; const bf16x2_t b = __builtin_convertvector(v, bf16x2_t); return __builtin_bit_cast(unsigned, b); }
; __device__ __forceinline__ f32x2 gelu_pk(f32x2 v) {
;     const f32x2 av = __builtin_elementwise_abs(v), d = av * 0.2316418882f + 1.0f;
;     f32x2 t; t.x = __builtin_amdgcn_rcpf(d.x); t.y = __builtin_amdgcn_rcpf(d.y);
;     f32x2 q = t * 0.5307027145f + (-0.7265760135f); q = q * t + 0.7107068705f; q = q * t + (-0.142248368f); q = q * t + 0.127414796f; q = q * t;
;     const f32x2 s = (v * v) * (-0.72134752044f);
;     f32x2 e; e.x = __builtin_amdgcn_exp2f(s.x); e.y = __builtin_amdgcn_exp2f(s.y);
;     const f32x2 m = v * (q * e), r = v - m;
;     f32x2 o; o.x = v.x < 0.f ? m.x : r.x; o.y = v.y < 0.f ? m.y : r.y; return o;
; __device__ __forceinline__ void conv2d_phase(const Frame& F, int l, bool with_ctx, bool dry) {
;     ...
; #pragma unroll
;         for (int t = 0; t < 8; ++t) {
;             f32x4 a = bias4;
; #pragma unroll
;             for (int dy = 0; dy < 3; ++dy)
; #pragma unroll
;                 for (int dx = 0; dx < 3; ++dx) {
;                     const u32x2 x = u[dy][t + dx]; const f32x4 ww = w[dy * 3 + dx];
;                     a.x += ww.x * bflo(x.x); a.y += ww.y * bfhi(x.x); a.z += ww.z * bflo(x.y); a.w += ww.w * bfhi(x.y);
;                 }
;             const f32x2 g0 = gelu_pk((f32x2){a.x, a.y}), g1 = gelu_pk((f32x2){a.z, a.w});
;             u32x2 o; o.x = pk2(g0.x * bflo(vv[t].x), g0.y * bfhi(vv[t].x)); o.y = pk2(g1.x * bflo(vv[t].y), g1.y * bfhi(vv[t].y));
;             bf16_t* vp = UV + (size_t)(tok0 + t) * NUP + FFN + ch;
;             if (!dry) *(u32x2*)vp = o; else asm volatile("" :: "v"(o));
	v_pk_fma_f32 v[134:135], v[34:35], v[110:111], v[38:39]
	global_load_dwordx2 v[96:97], v[74:75], off offset:512
	v_add_co_u32_e32 v74, vcc, s28, v68
	s_mov_b32 s28, 0x9000
	s_nop 0
	v_addc_co_u32_e32 v75, vcc, 0, v69, vcc
	global_load_dwordx2 v[98:99], v[74:75], off offset:3584
	v_add_co_u32_e32 v74, vcc, s28, v68
	s_mov_b32 s28, 0xc000
	s_nop 0
	v_addc_co_u32_e32 v75, vcc, 0, v69, vcc
	global_load_dwordx2 v[86:87], v[74:75], off offset:2560
	v_add_co_u32_e32 v74, vcc, s28, v68
	s_mov_b32 s28, 0xf000
	s_nop 0
	v_addc_co_u32_e32 v75, vcc, 0, v69, vcc
	global_load_dwordx2 v[76:77], v[74:75], off offset:1536
	v_add_co_u32_e32 v74, vcc, s28, v68
	s_mov_b32 s28, 0x11000
	s_nop 0
	v_addc_co_u32_e32 v75, vcc, 0, v69, vcc
	global_load_dwordx2 v[88:89], v[74:75], off offset:512
	v_add_co_u32_e32 v74, vcc, s28, v68
	s_mov_b32 s28, 0x14000
	s_nop 0
	v_addc_co_u32_e32 v75, vcc, 0, v69, vcc
	global_load_dwordx2 v[78:79], v[74:75], off offset:3584
	v_add_co_u32_e32 v74, vcc, s28, v68
	v_lshlrev_b32_e32 v110, 16, v108
	s_nop 0
	v_addc_co_u32_e32 v75, vcc, 0, v69, vcc
	global_load_dwordx2 v[74:75], v[74:75], off offset:2560
	v_and_b32_e32 v111, 0xffff0000, v108
	v_pk_fma_f32 v[136:137], v[36:37], v[110:111], v[40:41]
	v_lshlrev_b32_e32 v110, 16, v105
	v_and_b32_e32 v111, 0xffff0000, v105
	v_lshlrev_b32_e32 v142, 16, v133
	v_and_b32_e32 v143, 0xffff0000, v133
	v_lshlrev_b32_e32 v144, 16, v132
	v_and_b32_e32 v145, 0xffff0000, v132
	v_pk_fma_f32 v[132:133], v[18:19], v[116:117], v[134:135]
	v_and_b32_e32 v105, 0xffff0000, v115
	v_pk_fma_f32 v[132:133], v[22:23], v[110:111], v[132:133]
	v_lshlrev_b32_e32 v122, 16, v126
	v_pk_fma_f32 v[132:133], v[26:27], v[138:139], v[132:133]
	v_and_b32_e32 v123, 0xffff0000, v126
	v_pk_fma_f32 v[132:133], v[30:31], v[120:121], v[132:133]
	v_lshlrev_b32_e32 v108, 16, v131
	v_pk_fma_f32 v[132:133], v[10:11], v[104:105], v[132:133]
	v_and_b32_e32 v109, 0xffff0000, v131
	v_pk_fma_f32 v[132:133], v[14:15], v[142:143], v[132:133]
	s_mov_b32 s28, 0x3e6d3388
	v_pk_fma_f32 v[132:133], v[2:3], v[122:123], v[132:133]
	v_lshlrev_b32_e32 v114, 16, v130
	v_pk_fma_f32 v[132:133], v[6:7], v[108:109], v[132:133]
	v_and_b32_e32 v115, 0xffff0000, v130
	v_and_b32_e32 v135, 0x7fffffff, v133
	v_and_b32_e32 v134, 0x7fffffff, v132
	v_pk_fma_f32 v[134:135], v[134:135], s[28:29], 1.0 op_sel_hi:[1,0,0]
	v_pk_fma_f32 v[130:131], v[20:21], v[118:119], v[136:137]
	v_rcp_f32_e32 v134, v134
	v_rcp_f32_e32 v135, v135
	v_pk_fma_f32 v[130:131], v[24:25], v[112:113], v[130:131]
	s_mov_b32 s38, 0xbf3a00e3
	v_pk_fma_f32 v[130:131], v[28:29], v[140:141], v[130:131]
	v_mov_b64_e32 v[136:137], s[38:39]
	v_pk_mul_f32 v[140:141], v[132:133], v[132:133]
	v_pk_fma_f32 v[130:131], v[32:33], v[124:125], v[130:131]
	v_pk_fma_f32 v[138:139], v[134:135], s[36:37], v[136:137] op_sel_hi:[1,0,0]
	s_mov_b32 s40, 0x3f35f0e3
	v_pk_mul_f32 v[140:141], v[140:141], s[46:47] op_sel_hi:[1,0]
	v_pk_fma_f32 v[130:131], v[12:13], v[106:107], v[130:131]
	v_pk_fma_f32 v[138:139], v[134:135], v[138:139], s[40:41] op_sel_hi:[1,1,0]
	s_mov_b32 s42, 0xbe11a98e
	v_exp_f32_e32 v140, v140
	v_exp_f32_e32 v141, v141
	v_lshlrev_b32_e32 v126, 16, v127
	v_and_b32_e32 v127, 0xffff0000, v127
	v_pk_fma_f32 v[130:131], v[16:17], v[144:145], v[130:131]
	v_pk_fma_f32 v[138:139], v[134:135], v[138:139], s[42:43] op_sel_hi:[1,1,0]
	s_mov_b32 s44, 0x3e027906
	v_pk_fma_f32 v[130:131], v[4:5], v[126:127], v[130:131]
	v_pk_fma_f32 v[138:139], v[134:135], v[138:139], s[44:45] op_sel_hi:[1,1,0]
	v_pk_fma_f32 v[130:131], v[8:9], v[114:115], v[130:131]
	v_pk_mul_f32 v[134:135], v[134:135], v[138:139]
	v_cmp_gt_f32_e32 vcc, 0, v133
	v_pk_mul_f32 v[134:135], v[140:141], v[134:135]
	v_and_b32_e32 v141, 0x7fffffff, v131
	v_and_b32_e32 v140, 0x7fffffff, v130
	v_pk_fma_f32 v[140:141], v[140:141], s[28:29], 1.0 op_sel_hi:[1,0,0]
	v_pk_mul_f32 v[138:139], v[132:133], v[134:135]
	v_rcp_f32_e32 v140, v140
	v_rcp_f32_e32 v141, v141
	v_pk_fma_f32 v[134:135], v[132:133], v[134:135], v[132:133] neg_lo:[1,0,0] neg_hi:[1,0,0]
	s_mov_b64 s[30:31], -1
	v_cndmask_b32_e32 v133, v135, v139, vcc
	v_cmp_gt_f32_e32 vcc, 0, v132
	s_waitcnt vmcnt(8)
	v_and_b32_e32 v139, 0xffff0000, v102
	v_cndmask_b32_e32 v132, v134, v138, vcc
	v_pk_fma_f32 v[134:135], v[140:141], s[36:37], v[136:137] op_sel_hi:[1,0,0]
	v_pk_mul_f32 v[136:137], v[130:131], v[130:131]
	v_pk_fma_f32 v[134:135], v[140:141], v[134:135], s[40:41] op_sel_hi:[1,1,0]
	v_pk_mul_f32 v[136:137], v[136:137], s[46:47] op_sel_hi:[1,0]
	v_pk_fma_f32 v[134:135], v[140:141], v[134:135], s[42:43] op_sel_hi:[1,1,0]
	v_exp_f32_e32 v136, v136
	v_exp_f32_e32 v137, v137
	v_pk_fma_f32 v[134:135], v[140:141], v[134:135], s[44:45] op_sel_hi:[1,1,0]
	v_cmp_gt_f32_e32 vcc, 0, v131
	v_pk_mul_f32 v[134:135], v[140:141], v[134:135]
	v_lshlrev_b32_e32 v138, 16, v102
	v_pk_mul_f32 v[134:135], v[136:137], v[134:135]
	v_pk_mul_f32 v[132:133], v[132:133], v[138:139]
	v_pk_mul_f32 v[136:137], v[130:131], v[134:135]
	v_pk_fma_f32 v[134:135], v[130:131], v[134:135], v[130:131] neg_lo:[1,0,0] neg_hi:[1,0,0]
	v_cvt_pk_bf16_f32 v102, v132, v133
	v_cndmask_b32_e32 v131, v135, v137, vcc
	v_cmp_gt_f32_e32 vcc, 0, v130
	v_lshlrev_b32_e32 v132, 16, v103
	v_and_b32_e32 v133, 0xffff0000, v103
	v_cndmask_b32_e32 v130, v134, v136, vcc
	v_pk_mul_f32 v[130:131], v[130:131], v[132:133]
	s_and_b64 vcc, exec, s[48:49]
	v_cvt_pk_bf16_f32 v103, v130, v131
	s_cbranch_vccz .LBB0_2039
	s_mov_b64 s[30:31], 0
